# attention: scalar-base stage DMAs + unit-boundary counted waits (lambda preloaded, first-tile DMAs before the bias-row wait), on top of v165
# baseline (speedup 1.0000x reference)
.LBB0_1129:
	v_and_b32_e32 v2, 64, v164
	v_xor_b32_e32 v1, 16, v164
	v_add_u32_e32 v3, 64, v2
	v_cmp_lt_i32_e32 vcc, v1, v3
	v_xor_b32_e32 v84, 32, v164
	s_waitcnt lgkmcnt(0)
	s_barrier
	global_load_dword v131, v0, s[14:15]
	v_cndmask_b32_e32 v1, v164, v1, vcc
	v_lshlrev_b32_e32 v1, 2, v1
	ds_bpermute_b32 v2, v1, v116
	v_cmp_lt_i32_e32 vcc, v84, v3
	s_add_i32 s76, s76, s33
	s_cmpk_gt_i32 s76, 0x3ff
	v_cndmask_b32_e32 v3, v164, v84, vcc
	s_waitcnt lgkmcnt(0)
	v_add_f32_e32 v2, v116, v2
	v_lshlrev_b32_e32 v85, 2, v3
	ds_bpermute_b32 v3, v85, v2
	s_cselect_b64 s[70:71], -1, 0
	s_cmpk_lt_i32 s76, 0x400
	s_mov_b32 s93, s91
	s_mov_b32 s92, s90
	s_cbranch_scc0 .Latt_nonext_w
	s_and_b32 s48, s76, 7
	s_cmpk_gt_u32 s76, 0xff
	s_mov_b64 s[0:1], -1
	s_cbranch_scc0 .LBB0_1132
	s_ashr_i32 s0, s76, 8
	s_xor_b32 s1, s48, 23
	s_or_b32 s7, s48, 8
	s_cmp_eq_u32 s0, 2
	s_cselect_b32 s1, s1, s7
	s_cmp_eq_u32 s0, 1
	s_cselect_b32 s94, s48, s1
	s_mov_b64 s[0:1], 0

.LBB0_1134:
	s_lshl_b32 s0, s94, 6
	s_or_b32 s87, s0, s78
	s_lshl_b32 s0, s76, 5
	s_bfe_u32 s92, s76, 0x30003
	s_and_b32 s0, s0, 0x1800
	s_add_i32 s93, s87, s0
	s_lshl_b32 s1, s0, 12
	s_lshl_b32 s7, s92, 22
	s_add_u32 s7, s74, s7
	s_addc_u32 s26, s75, 0
	s_lshl_b32 s50, s92, 9
	v_add_lshl_u32 v4, s50, v226, 2
	global_load_dword v84, v4, s[8:9]
	v_mov_b32_e32 v5, v0
	v_or_b32_e32 v4, s93, v150
	v_lshlrev_b64 v[4:5], 12, v[4:5]
	s_add_u32 s1, s72, s1
	v_lshl_add_u64 v[4:5], s[18:19], 0, v[4:5]
	s_addc_u32 s27, s73, 0
	s_mov_b32 s69, s51
	v_lshl_add_u64 v[4:5], v[4:5], 0, s[50:51]
	s_add_u32 s52, s1, s50
	v_mov_b32_e32 v143, v0
	v_lshl_add_u64 v[4:5], v[4:5], 0, s[68:69]
	s_addc_u32 s53, s27, 0
	s_mov_b32 m0, s79
	v_lshl_add_u64 v[16:17], v[4:5], 0, v[142:143]
	v_lshl_add_u64 v[86:87], s[52:53], 0, v[132:133]
	s_lshl_b32 s0, s0, 1
	global_load_dwordx4 v[4:7], v[16:17], off
	global_load_dwordx4 v[8:11], v[16:17], off offset:64
	global_load_dwordx4 v[12:15], v[16:17], off offset:128
	s_nop 0
	global_load_dwordx4 v[16:19], v[16:17], off offset:192
	v_lshl_add_u64 v[88:89], v[86:87], 0, s[46:47]
	s_add_u32 s48, s7, s0
	v_lshl_add_u64 v[90:91], v[86:87], 0, s[42:43]
	v_lshl_add_u64 v[92:93], v[86:87], 0, s[40:41]
	s_addc_u32 s49, s26, 0
	v_lshl_add_u64 v[94:95], s[48:49], 0, v[134:135]
	v_lshl_add_u64 v[96:97], v[94:95], 0, s[36:37]
	v_lshl_add_u64 v[98:99], v[94:95], 0, s[34:35]
	v_lshl_add_u64 v[100:101], v[94:95], 0, s[30:31]
	s_add_i32 s69, s94, 1
	global_load_lds_dwordx4 v[86:87], off
	s_mov_b32 m0, s77
	s_nop 0
	global_load_lds_dwordx4 v[88:89], off
	s_mov_b32 m0, s82
	s_nop 0
	global_load_lds_dwordx4 v[90:91], off
	s_mov_b32 m0, s83
	s_nop 0
	global_load_lds_dwordx4 v[92:93], off
	s_mov_b32 m0, s80
	s_nop 0
	global_load_lds_dwordx4 v[94:95], off
	s_mov_b32 m0, s84
	s_nop 0
	global_load_lds_dwordx4 v[96:97], off
	s_mov_b32 m0, s85
	s_nop 0
	global_load_lds_dwordx4 v[98:99], off
	s_mov_b32 m0, s86
	s_nop 0
	global_load_lds_dwordx4 v[100:101], off
	s_waitcnt vmcnt(12)
	ds_write_b32 v151, v84
	s_branch .LBB0_1135

.LBB0_1135:
	s_andn2_b64 vcc, exec, s[10:11]
	s_waitcnt lgkmcnt(0)
	v_add_f32_e32 v2, v2, v3
	s_cbranch_vccnz .LBB0_1137
	s_waitcnt vmcnt(13)
	v_div_scale_f32 v84, s[0:1], v2, v2, v131
	v_rcp_f32_e32 v86, v84
	v_div_scale_f32 v87, vcc, v131, v2, v131
	v_fma_f32 v88, -v84, v86, 1.0
	v_fmac_f32_e32 v86, v88, v86
	v_mul_f32_e32 v88, v87, v86
	v_fma_f32 v89, -v84, v88, v87
	v_fmac_f32_e32 v88, v89, v86
	v_fma_f32 v84, -v84, v88, v87
	v_div_fmas_f32 v84, v84, v86, v88
	v_div_fixup_f32 v84, v84, v2, v131
	v_pk_mul_f32 v[88:89], v[82:83], v[84:85] op_sel_hi:[1,0]
	v_pk_mul_f32 v[86:87], v[80:81], v[84:85] op_sel_hi:[1,0]
	v_pk_mul_f32 v[92:93], v[78:79], v[84:85] op_sel_hi:[1,0]
	v_pk_mul_f32 v[90:91], v[76:77], v[84:85] op_sel_hi:[1,0]
	v_pk_mul_f32 v[96:97], v[74:75], v[84:85] op_sel_hi:[1,0]
	v_pk_mul_f32 v[94:95], v[72:73], v[84:85] op_sel_hi:[1,0]
	v_pk_mul_f32 v[100:101], v[70:71], v[84:85] op_sel_hi:[1,0]
	v_pk_mul_f32 v[98:99], v[68:69], v[84:85] op_sel_hi:[1,0]
	v_pk_mul_f32 v[104:105], v[66:67], v[84:85] op_sel_hi:[1,0]
	v_pk_mul_f32 v[102:103], v[64:65], v[84:85] op_sel_hi:[1,0]
	v_pk_mul_f32 v[108:109], v[62:63], v[84:85] op_sel_hi:[1,0]
	v_pk_mul_f32 v[106:107], v[60:61], v[84:85] op_sel_hi:[1,0]
	v_pk_mul_f32 v[112:113], v[58:59], v[84:85] op_sel_hi:[1,0]
	v_pk_mul_f32 v[110:111], v[56:57], v[84:85] op_sel_hi:[1,0]
	v_pk_mul_f32 v[116:117], v[54:55], v[84:85] op_sel_hi:[1,0]
	v_pk_mul_f32 v[114:115], v[52:53], v[84:85] op_sel_hi:[1,0]
	v_pk_mul_f32 v[120:121], v[50:51], v[84:85] op_sel_hi:[1,0]
	v_pk_mul_f32 v[118:119], v[48:49], v[84:85] op_sel_hi:[1,0]
	v_pk_mul_f32 v[124:125], v[46:47], v[84:85] op_sel_hi:[1,0]
	v_pk_mul_f32 v[122:123], v[44:45], v[84:85] op_sel_hi:[1,0]
	v_pk_mul_f32 v[128:129], v[42:43], v[84:85] op_sel_hi:[1,0]
	v_pk_mul_f32 v[126:127], v[40:41], v[84:85] op_sel_hi:[1,0]
	v_pk_mul_f32 v[148:149], v[38:39], v[84:85] op_sel_hi:[1,0]
	v_pk_mul_f32 v[146:147], v[36:37], v[84:85] op_sel_hi:[1,0]
	v_pk_mul_f32 v[168:169], v[34:35], v[84:85] op_sel_hi:[1,0]
	v_pk_mul_f32 v[166:167], v[32:33], v[84:85] op_sel_hi:[1,0]
	v_pk_mul_f32 v[172:173], v[30:31], v[84:85] op_sel_hi:[1,0]
	v_pk_mul_f32 v[170:171], v[28:29], v[84:85] op_sel_hi:[1,0]
	v_pk_mul_f32 v[176:177], v[26:27], v[84:85] op_sel_hi:[1,0]
	v_pk_mul_f32 v[174:175], v[24:25], v[84:85] op_sel_hi:[1,0]
	v_pk_mul_f32 v[180:181], v[22:23], v[84:85] op_sel_hi:[1,0]
	v_pk_mul_f32 v[178:179], v[20:21], v[84:85] op_sel_hi:[1,0]
	ds_write_b128 v152, v[86:89]
	ds_write_b128 v152, v[90:93] offset:1024
	ds_write_b128 v152, v[94:97] offset:2048
	ds_write_b128 v152, v[98:101] offset:3072
	ds_write_b128 v152, v[102:105] offset:4096
	ds_write_b128 v152, v[106:109] offset:5120
	ds_write_b128 v152, v[110:113] offset:6144
	ds_write_b128 v152, v[114:117] offset:7168
	ds_write_b128 v152, v[118:121] offset:8192
	ds_write_b128 v152, v[122:125] offset:9216
	ds_write_b128 v152, v[126:129] offset:10240
	ds_write_b128 v152, v[146:149] offset:11264
	ds_write_b128 v152, v[166:169] offset:12288
	ds_write_b128 v152, v[170:173] offset:13312
	ds_write_b128 v152, v[174:177] offset:14336
	ds_write_b128 v152, v[178:181] offset:15360
